# diff work queue: next unit index requested at the start of the unit epilogue (atomic round trip and output-store drain no longer serialise the next unit's start)
# speedup vs baseline: 1.0037x; 1.0037x over previous
; #define LAS __attribute__((address_space(3)))
; #define INP(i) (*(const float* const volatile __attribute__((address_space(4)))*)((const __attribute__((address_space(4))) char*)__builtin_amdgcn_kernarg_segment_ptr() + 8 * (i)))
; __global__ void __launch_bounds__(NTHREADS, 2) mega_fwd(Args args) {
;     ...
;                 float gq = 0.f, gk = 0.f;
;                 { const float* g1 = INP(16); const float* g2 = INP(17);
;                   for (int i = 0; i < 64; ++i) { gq = fmaxf(gq, fabsf(g1[i])); gk = fmaxf(gk, fabsf(g2[i])); } }
;                 const float Bq = 8.0f * gq * gk * LOG2E * 1.05f;
;                 unsigned* qctr = (unsigned*)(ws + S_CTL) + 3600;
;                 volatile LAS unsigned* qslot = (volatile LAS unsigned*)(lds + LDS_ST_OFF + 8);
;                 for (;;) {
;                     if (threadIdx.x == 0) *qslot = __hip_atomic_fetch_add(qctr, 1u, __ATOMIC_RELAXED, __HIP_MEMORY_SCOPE_AGENT);
.LBB0_921:
	s_add_u32 s2, s6, s10
	s_addc_u32 s3, s7, s11
	global_load_dwordx4 v[4:7], v1, s[2:3] offset:16
	global_load_dwordx4 v[8:11], v1, s[2:3]
	s_waitcnt lgkmcnt(0)
	s_add_u32 s2, s8, s10
	s_addc_u32 s3, s9, s11
	global_load_dwordx4 v[12:15], v1, s[2:3]
	global_load_dwordx4 v[16:19], v1, s[2:3] offset:16
	s_add_u32 s10, s10, 32
	s_addc_u32 s11, s11, 0
	s_cmpk_eq_i32 s10, 0x100
	s_waitcnt vmcnt(0)
	v_max3_f32 v2, v2, |v8|, |v9|
	v_max3_f32 v2, v2, |v10|, |v11|
	v_max3_f32 v0, v0, |v12|, |v13|
	v_max3_f32 v0, v0, |v14|, |v15|
	v_max3_f32 v2, v2, |v4|, |v5|
	v_max3_f32 v0, v0, |v16|, |v17|
	v_max3_f32 v2, v2, |v6|, |v7|
	v_max3_f32 v0, v0, |v18|, |v19|
	s_cbranch_scc0 .LBB0_921
	v_mul_f32_e32 v2, 0x41000000, v2
	v_mul_f32_e32 v0, v0, v2
	v_mul_f32_e32 v0, 0x3fb8aa3b, v0
	v_mul_f32_e32 v0, 0x3f866666, v0
	v_add_f32_e32 v2, v0, v0
	s_mov_b32 s2, 0x42700000
	v_fmaak_f32 v221, 2.0, v0, 0x43180000
	v_cmp_gt_f32_e64 s[40:41], s2, v2
	v_cmp_ngt_f32_e64 s[42:43], s2, v2
	v_readlane_b32 s12, v255, 36
	s_mov_b64 s[98:99], exec
	v_readlane_b32 s100, v252, 4
	v_readlane_b32 s101, v252, 5
	s_nop 3
	s_mov_b64 exec, s[100:101]
	v_readlane_b32 s100, v254, 16
	v_readlane_b32 s101, v254, 17
	v_mov_b32_e32 v237, 1
	v_mov_b32_e32 v238, 0
	s_nop 4
	global_atomic_add v236, v238, v237, s[100:101] sc0
	s_mov_b64 exec, s[98:99]
	s_waitcnt vmcnt(0)
	s_branch .LBB0_926

; __device__ __forceinline__ unsigned pk2(float lo, float hi) { f32x2 v = {lo, hi}; bf16x2_t b = __builtin_convertvector(v, bf16x2_t); return __builtin_bit_cast(unsigned, b); }
; __device__ __forceinline__ float shfl_xor_l(float v, int o, int lane) { return __builtin_bit_cast(float, __builtin_amdgcn_ds_bpermute((lane ^ o) << 2, __builtin_bit_cast(int, v))); }
; template <int DQK, int DV, int FLAGS, int qp, int kp, int vts, int op> ...
;     ...
;     float lt = l + shfl_xor_l(l, 32, lane);
;     if (FLAGS & AF_SINK) lt += __builtin_amdgcn_exp2f(sink2 - m);
;     const float inv = 1.0f / lt;
;     bf16* orow = O + (size_t)(32 * wave + r32) * op + 4 * hi;
; #pragma unroll
;     for (int d = 0; d < NDB; ++d)
; #pragma unroll
;         for (int g = 0; g < 4; ++g) {
;             u32x2 w; w.x = pk2(o[d][4 * g] * inv, o[d][4 * g + 1] * inv); w.y = pk2(o[d][4 * g + 2] * inv, o[d][4 * g + 3] * inv);
;             *(u32x2*)(orow + 32 * d + 8 * g) = w;
;         }
; __global__ void __launch_bounds__(NTHREADS, 2) mega_fwd(Args args) {
;     ...
;                     if (threadIdx.x == 0) *qslot = __hip_atomic_fetch_add(qctr, 1u, __ATOMIC_RELAXED, __HIP_MEMORY_SCOPE_AGENT);
.LBB0_924:
	s_mov_b64 s[98:99], exec
	v_readlane_b32 s100, v252, 4
	v_readlane_b32 s101, v252, 5
	s_nop 3
	s_mov_b64 exec, s[100:101]
	v_readlane_b32 s100, v254, 16
	v_readlane_b32 s101, v254, 17
	v_mov_b32_e32 v237, 1
	v_mov_b32_e32 v238, 0
	s_nop 4
	global_atomic_add v236, v238, v237, s[100:101] sc0
	s_mov_b64 exec, s[98:99]
	ds_bpermute_b32 v0, v80, v199
	s_cmp_eq_u32 s4, 0
	s_mov_b32 s2, 0x8200000
	v_readlane_b32 s8, v252, 0
	s_cselect_b32 s2, s2, 0xc200000
	v_readlane_b32 s10, v252, 2
	v_readlane_b32 s11, v252, 3
	s_add_u32 s2, s10, s2
	s_addc_u32 s4, s11, 0
	s_waitcnt lgkmcnt(0)
	v_add_f32_e32 v0, v199, v0
	s_add_u32 s6, s2, s30
	s_waitcnt vmcnt(3)
	v_div_scale_f32 v4, s[2:3], v0, v0, 1.0
	v_rcp_f32_e32 v5, v4
	s_addc_u32 s3, s4, s31
	s_add_u32 s2, s6, s5
	v_lshlrev_b64 v[2:3], 10, v[176:177]
	s_waitcnt vmcnt(2)
	v_fma_f32 v6, -v4, v5, 1.0
	v_fmac_f32_e32 v5, v6, v5
	v_div_scale_f32 v6, vcc, 1.0, v0, 1.0
	v_mul_f32_e32 v7, v6, v5
	v_fma_f32 v8, -v4, v7, v6
	v_fmac_f32_e32 v7, v8, v5
	v_fma_f32 v4, -v4, v7, v6
	v_div_fmas_f32 v4, v4, v5, v7
	s_addc_u32 s3, s3, 0
	v_div_fixup_f32 v0, v4, v0, 1.0
	v_lshl_add_u64 v[2:3], v[2:3], 1, s[2:3]
	v_mov_b32_e32 v199, v1
	v_pk_mul_f32 v[4:5], v[64:65], v[0:1] op_sel_hi:[1,0]
	v_pk_mul_f32 v[6:7], v[66:67], v[0:1] op_sel_hi:[1,0]
	v_lshl_add_u64 v[2:3], v[2:3], 0, v[198:199]
	v_cvt_pk_bf16_f32 v4, v4, v5
	v_cvt_pk_bf16_f32 v5, v6, v7
	global_store_dwordx2 v[2:3], v[4:5], off
	v_pk_mul_f32 v[4:5], v[68:69], v[0:1] op_sel_hi:[1,0]
	v_pk_mul_f32 v[6:7], v[70:71], v[0:1] op_sel_hi:[1,0]
	v_cvt_pk_bf16_f32 v4, v4, v5
	v_cvt_pk_bf16_f32 v5, v6, v7
	global_store_dwordx2 v[2:3], v[4:5], off offset:16
	v_pk_mul_f32 v[4:5], v[72:73], v[0:1] op_sel_hi:[1,0]
	v_pk_mul_f32 v[6:7], v[74:75], v[0:1] op_sel_hi:[1,0]
	v_cvt_pk_bf16_f32 v4, v4, v5
	v_cvt_pk_bf16_f32 v5, v6, v7
	global_store_dwordx2 v[2:3], v[4:5], off offset:32
	v_pk_mul_f32 v[4:5], v[76:77], v[0:1] op_sel_hi:[1,0]
	v_pk_mul_f32 v[6:7], v[78:79], v[0:1] op_sel_hi:[1,0]
	v_cvt_pk_bf16_f32 v4, v4, v5
	v_cvt_pk_bf16_f32 v5, v6, v7
	global_store_dwordx2 v[2:3], v[4:5], off offset:48
	v_pk_mul_f32 v[4:5], v[48:49], v[0:1] op_sel_hi:[1,0]
	v_pk_mul_f32 v[6:7], v[50:51], v[0:1] op_sel_hi:[1,0]
	v_cvt_pk_bf16_f32 v4, v4, v5
	v_cvt_pk_bf16_f32 v5, v6, v7
	global_store_dwordx2 v[2:3], v[4:5], off offset:64
	v_pk_mul_f32 v[4:5], v[52:53], v[0:1] op_sel_hi:[1,0]
	v_pk_mul_f32 v[6:7], v[54:55], v[0:1] op_sel_hi:[1,0]
	v_cvt_pk_bf16_f32 v4, v4, v5
	v_cvt_pk_bf16_f32 v5, v6, v7
	global_store_dwordx2 v[2:3], v[4:5], off offset:80
	v_pk_mul_f32 v[4:5], v[56:57], v[0:1] op_sel_hi:[1,0]
	v_pk_mul_f32 v[6:7], v[58:59], v[0:1] op_sel_hi:[1,0]
	v_cvt_pk_bf16_f32 v4, v4, v5
	v_cvt_pk_bf16_f32 v5, v6, v7
	global_store_dwordx2 v[2:3], v[4:5], off offset:96
	v_pk_mul_f32 v[4:5], v[60:61], v[0:1] op_sel_hi:[1,0]
	v_pk_mul_f32 v[6:7], v[62:63], v[0:1] op_sel_hi:[1,0]
	v_cvt_pk_bf16_f32 v4, v4, v5
	v_cvt_pk_bf16_f32 v5, v6, v7
	global_store_dwordx2 v[2:3], v[4:5], off offset:112
	v_pk_mul_f32 v[4:5], v[32:33], v[0:1] op_sel_hi:[1,0]
	v_pk_mul_f32 v[6:7], v[34:35], v[0:1] op_sel_hi:[1,0]
	v_cvt_pk_bf16_f32 v4, v4, v5
	v_cvt_pk_bf16_f32 v5, v6, v7
	global_store_dwordx2 v[2:3], v[4:5], off offset:128
	v_pk_mul_f32 v[4:5], v[36:37], v[0:1] op_sel_hi:[1,0]
	v_pk_mul_f32 v[6:7], v[38:39], v[0:1] op_sel_hi:[1,0]
	v_cvt_pk_bf16_f32 v4, v4, v5
	v_cvt_pk_bf16_f32 v5, v6, v7
	global_store_dwordx2 v[2:3], v[4:5], off offset:144
	v_pk_mul_f32 v[4:5], v[40:41], v[0:1] op_sel_hi:[1,0]
	v_pk_mul_f32 v[6:7], v[42:43], v[0:1] op_sel_hi:[1,0]
	v_cvt_pk_bf16_f32 v4, v4, v5
	v_cvt_pk_bf16_f32 v5, v6, v7
	global_store_dwordx2 v[2:3], v[4:5], off offset:160
	v_pk_mul_f32 v[4:5], v[44:45], v[0:1] op_sel_hi:[1,0]
	v_pk_mul_f32 v[6:7], v[46:47], v[0:1] op_sel_hi:[1,0]
	v_cvt_pk_bf16_f32 v4, v4, v5
	v_cvt_pk_bf16_f32 v5, v6, v7
	global_store_dwordx2 v[2:3], v[4:5], off offset:176
	v_pk_mul_f32 v[4:5], v[16:17], v[0:1] op_sel_hi:[1,0]
	v_pk_mul_f32 v[6:7], v[18:19], v[0:1] op_sel_hi:[1,0]
	v_cvt_pk_bf16_f32 v4, v4, v5
	v_cvt_pk_bf16_f32 v5, v6, v7
	global_store_dwordx2 v[2:3], v[4:5], off offset:192
	v_pk_mul_f32 v[4:5], v[20:21], v[0:1] op_sel_hi:[1,0]
	v_pk_mul_f32 v[6:7], v[22:23], v[0:1] op_sel_hi:[1,0]
	v_cvt_pk_bf16_f32 v4, v4, v5
	v_cvt_pk_bf16_f32 v5, v6, v7
	global_store_dwordx2 v[2:3], v[4:5], off offset:208
	v_pk_mul_f32 v[4:5], v[24:25], v[0:1] op_sel_hi:[1,0]
	v_pk_mul_f32 v[6:7], v[26:27], v[0:1] op_sel_hi:[1,0]
	v_cvt_pk_bf16_f32 v4, v4, v5
	v_cvt_pk_bf16_f32 v5, v6, v7
	global_store_dwordx2 v[2:3], v[4:5], off offset:224
	v_pk_mul_f32 v[4:5], v[28:29], v[0:1] op_sel_hi:[1,0]
	v_pk_mul_f32 v[6:7], v[30:31], v[0:1] op_sel_hi:[1,0]
	v_readlane_b32 s12, v255, 36
	v_cvt_pk_bf16_f32 v4, v4, v5
	v_cvt_pk_bf16_f32 v5, v6, v7
	s_mov_b64 s[6:7], 0
	v_readlane_b32 s9, v252, 1
	global_store_dwordx2 v[2:3], v[4:5], off offset:240

; __global__ void __launch_bounds__(NTHREADS, 2) mega_fwd(Args args) {
;     ...
;                     if (threadIdx.x == 0) *qslot = __hip_atomic_fetch_add(qctr, 1u, __ATOMIC_RELAXED, __HIP_MEMORY_SCOPE_AGENT);
;                     __syncthreads();
;                     const int j = (int)*qslot;
.LBB0_926:
	s_mov_b64 s[6:7], exec
	v_readlane_b32 s2, v252, 4
	v_readlane_b32 s3, v252, 5
	s_and_b64 s[2:3], s[6:7], s[2:3]
	s_mov_b64 exec, s[2:3]
	s_cbranch_execz .LBB0_930
	s_waitcnt vmcnt(16)
	v_mov_b32_e32 v2, s12
	ds_write_b32 v2, v236
